# P4 position-DFT gemm8s3 k-loops: 2-set fragment ping-pong, rotated barrier, unmasked slim LDS-DMA
# speedup vs baseline: 1.0173x; 1.0016x over previous
; DI void wait_vm0() { asm volatile("s_waitcnt vmcnt(0)" ::: "memory"); }
; DI void bar_() { __builtin_amdgcn_s_barrier(); }
; #define GLDS(gp, lp) __builtin_amdgcn_global_load_lds((const unsigned*)(gp), (__attribute__((address_space(3))) unsigned*)(lp), 16, 0, 0)
; #define SB_ __builtin_amdgcn_sched_barrier(0)
; #define LOADF(A_, B_, ks) do { const int po_ = (((ks) * 2 + hh) ^ sw) * 16; \
;       _Pragma("unroll") for (int tm = 0; tm < TM; ++tm) A_[tm] = *(const bf16x8*)(As + tm * 32 * LDR + po_); \
;       _Pragma("unroll") for (int tn = 0; tn < TN; ++tn) B_[tn] = *(const bf16x8*)(Bs + tn * 32 * LDR + po_); } while (0)
; template <int TM, int TN, int WM, int WN, bool SUMSQ, int NST, class AF, class BF, class AFN, class BFN>
; DI void gemm8x(f32x16 (&acc)[TM][TN], AF arow, BF brow, int K, char* smem, float& sumsq, bool pre, bool hasNext, AFN arowN, BFN browN) {
;     ...
;   if (NST == 3) {
;     char* l_ = smem + STAGE + t * 16; char* m_ = l_ + RA * LDR;
;     GLDS(pa0 + 64, l_); GLDS(pa1 + 64, l_ + 8192); GLDS(pa2 + 64, l_ + 16384); GLDS(pa3 + 64, l_ + 24576);
;     GLDS(pb0 + 64, m_); GLDS(pb1 + 64, m_ + 8192);
;     asm volatile("s_waitcnt vmcnt(6)" ::: "memory");
;   } else wait_vm0();
;   bar_();
;   const int nk = K >> 6;
;   const int sw = (r >> 1) & 7;
;   const int aoff = (wm * TM * 32 + r) * LDR, boff = RA * LDR + (wn * TN * 32 + r) * LDR;
;   auto compute = [&](const char* cur, char* nxt, bool issue, const bf16_t* q0, const bf16_t* q1, const bf16_t* q2, const bf16_t* q3,
;                      const bf16_t* s0, const bf16_t* s1, const bf16_t* s2, const bf16_t* s3) {
;     const char* As = cur + aoff;
;     const char* Bs = cur + boff;
;     char* l_ = nxt + t * 16; char* m_ = l_ + RA * LDR;
;     bf16x8 a0[TM], b0[TN], a1[TM], b1[TN];
;     ...
;     LOADF(a0, b0, 0);
;     LOADF(a1, b1, 1);
;     SB_;
;     if (issue) { if (a0v) GLDS(q0, l_); if (a1v) GLDS(q1, l_ + 8192); }
.LBB0_576:
	s_or_b64 exec, exec, s[50:51]
	v_ashrrev_i32_e32 v32, 6, v29
	v_lshrrev_b32_e32 v34, 30, v32
	v_readfirstlane_b32 s54, v30
	v_add_u32_e32 v34, v32, v34
	v_lshl_add_u64 v[8:9], v[8:9], 0, s[30:31]
	s_mov_b32 m0, s54
	v_ashrrev_i32_e32 v34, 2, v34
	global_load_lds_dwordx4 v[8:9], off
	v_lshl_add_u64 v[8:9], v[10:11], 0, s[30:31]
	v_readfirstlane_b32 s54, v31
	v_add_u32_e32 v10, 0x10000, v112
	v_mul_i32_i24_e32 v35, 4, v34
	s_mov_b32 m0, s54
	v_readfirstlane_b32 s54, v10
	v_add_u32_e32 v10, 0x12000, v112
	v_sub_u32_e32 v32, v32, v35
	v_add_u32_e32 v35, 0x14000, v112
	global_load_lds_dwordx4 v[8:9], off
	v_lshl_add_u64 v[8:9], v[14:15], 0, s[30:31]
	s_mov_b32 m0, s54
	v_readfirstlane_b32 s54, v10
	global_load_lds_dwordx4 v[8:9], off
	v_lshl_add_u64 v[8:9], v[18:19], 0, s[30:31]
	s_mov_b32 m0, s54
	v_readfirstlane_b32 s54, v35
	v_add_u32_e32 v10, 0x16000, v112
	global_load_lds_dwordx4 v[8:9], off
	v_lshl_add_u64 v[8:9], v[22:23], 0, s[30:31]
	s_mov_b32 m0, s54
	v_readfirstlane_b32 s54, v10
	global_load_lds_dwordx4 v[8:9], off
	v_lshl_add_u64 v[8:9], v[24:25], 0, s[30:31]
	s_mov_b32 m0, s54
	v_bfe_u32 v33, v29, 5, 1
	global_load_lds_dwordx4 v[8:9], off
	v_lshrrev_b32_e32 v8, 1, v29
	s_lshl_b32 s42, s42, 21
	s_lshl_b32 s50, s76, 12
	v_bfe_u32 v9, v29, 1, 3
	v_bitop3_b32 v8, v8, v33, 7 bitop3:0x6c
	s_add_i32 s42, s71, s42
	s_and_b32 s50, s50, 0x100000
	v_lshlrev_b32_e32 v116, 4, v8
	v_bitop3_b32 v8, v33, v9, 2 bitop3:0x36
	s_add_i32 s42, s42, s50
	v_lshlrev_b32_e32 v115, 4, v8
	v_bitop3_b32 v8, v33, v9, 4 bitop3:0x36
	s_lshl_b64 s[50:51], s[42:43], 1
	s_and_b32 s42, s89, 7
	v_lshlrev_b32_e32 v114, 4, v8
	v_bitop3_b32 v8, v33, v9, 6 bitop3:0x36
	s_lshl_b32 s42, s42, 19
	v_lshlrev_b32_e32 v113, 4, v8
	v_and_b32_e32 v8, 7, v28
	v_lshlrev_b32_e32 v168, 4, v8
	s_add_u32 s54, s69, s50
	v_lshl_add_u64 v[0:1], v[0:1], 0, v[168:169]
	s_addc_u32 s55, s70, s51
	v_lshl_add_u64 v[96:97], s[54:55], 0, v[0:1]
	v_lshl_add_u64 v[0:1], s[42:43], 0, v[26:27]
	v_lshl_add_u64 v[0:1], v[0:1], 0, v[168:169]
	v_lshl_add_u64 v[98:99], s[38:39], 0, v[0:1]
	v_lshl_add_u64 v[0:1], s[42:43], 0, v[20:21]
	v_lshl_add_u64 v[0:1], v[0:1], 0, v[168:169]
	v_lshl_add_u64 v[100:101], s[38:39], 0, v[0:1]
	v_lshl_add_u64 v[0:1], s[42:43], 0, v[16:17]
	v_lshl_add_u64 v[0:1], v[0:1], 0, v[168:169]
	v_lshl_add_u64 v[102:103], s[38:39], 0, v[0:1]
	v_lshl_add_u64 v[0:1], s[42:43], 0, v[12:13]
	v_lshl_add_u64 v[0:1], v[0:1], 0, v[168:169]
	v_lshl_add_u64 v[104:105], s[38:39], 0, v[0:1]
	v_lshl_add_u64 v[0:1], v[6:7], 0, v[168:169]
	v_lshl_add_u64 v[106:107], s[54:55], 0, v[0:1]
	v_lshl_add_u64 v[0:1], v[4:5], 0, v[168:169]
	s_waitcnt vmcnt(6)
	v_lshlrev_b32_e32 v10, 7, v29
	v_lshl_add_u64 v[108:109], s[54:55], 0, v[0:1]
	v_lshl_add_u64 v[0:1], v[2:3], 0, v[168:169]
	v_and_b32_e32 v119, 0xf80, v10
	v_lshlrev_b32_e32 v120, 13, v34
	v_lshl_add_u64 v[110:111], s[54:55], 0, v[0:1]
	v_mov_b32_e32 v0, 0
	v_lshl_or_b32 v117, v32, 13, v119
	v_or_b32_e32 v118, v119, v120
	s_mov_b32 s93, 0
	s_mov_b64 s[54:55], 0
	v_mov_b32_e32 v1, v0
	v_mov_b32_e32 v2, v0
	v_mov_b32_e32 v3, v0
	v_mov_b32_e32 v4, v0
	v_mov_b32_e32 v5, v0
	v_mov_b32_e32 v6, v0
	v_mov_b32_e32 v7, v0
	v_mov_b32_e32 v8, v0
	v_mov_b32_e32 v9, v0
	v_mov_b32_e32 v10, v0
	v_mov_b32_e32 v11, v0
	v_mov_b32_e32 v12, v0
	v_mov_b32_e32 v13, v0
	v_mov_b32_e32 v14, v0
	v_mov_b32_e32 v15, v0
	v_mov_b32_e32 v16, v0
	v_mov_b32_e32 v17, v0
	v_mov_b32_e32 v18, v0
	v_mov_b32_e32 v19, v0
	v_mov_b32_e32 v20, v0
	v_mov_b32_e32 v21, v0
	v_mov_b32_e32 v22, v0
	v_mov_b32_e32 v23, v0
	v_mov_b32_e32 v24, v0
	v_mov_b32_e32 v25, v0
	v_mov_b32_e32 v26, v0
	v_mov_b32_e32 v27, v0
	v_mov_b32_e32 v28, v0
	v_mov_b32_e32 v29, v0
	v_mov_b32_e32 v30, v0
	v_mov_b32_e32 v31, v0
	v_mov_b32_e32 v32, v0
	v_mov_b32_e32 v33, v0
	v_mov_b32_e32 v34, v0
	v_mov_b32_e32 v35, v0
	v_mov_b32_e32 v36, v0
	v_mov_b32_e32 v37, v0
	v_mov_b32_e32 v38, v0
	v_mov_b32_e32 v39, v0
	v_mov_b32_e32 v40, v0
	v_mov_b32_e32 v41, v0
	v_mov_b32_e32 v42, v0
	v_mov_b32_e32 v43, v0
	v_mov_b32_e32 v44, v0
	v_mov_b32_e32 v45, v0
	v_mov_b32_e32 v46, v0
	v_mov_b32_e32 v47, v0
	v_mov_b32_e32 v48, v0
	v_mov_b32_e32 v49, v0
	v_mov_b32_e32 v50, v0
	v_mov_b32_e32 v51, v0
	v_mov_b32_e32 v52, v0
	v_mov_b32_e32 v53, v0
	v_mov_b32_e32 v54, v0
	v_mov_b32_e32 v55, v0
	v_mov_b32_e32 v56, v0
	v_mov_b32_e32 v57, v0
	v_mov_b32_e32 v58, v0
	v_mov_b32_e32 v59, v0
	v_mov_b32_e32 v60, v0
	v_mov_b32_e32 v61, v0
	v_mov_b32_e32 v62, v0
	v_mov_b32_e32 v63, v0
	s_barrier
	v_readfirstlane_b32 s98, v112
	s_mul_i32 s99, s93, 0xc000
	v_add_u32_e32 v123, s99, v118
	v_add_u32_e32 v122, s99, v117
	s_add_i32 s99, s99, 0xffff4000
	s_cmp_lg_u32 s93, 0
	s_cselect_b32 s99, s99, 0x18000
	s_add_i32 s99, s99, s98
	v_add_u32_e32 v131, v123, v116
	v_add_u32_e32 v130, v122, v116
	ds_read_b128 v[88:91], v131 offset:32768
	ds_read_b128 v[84:87], v130
	ds_read_b128 v[92:95], v131 offset:36864
	ds_read_b128 v[80:83], v130 offset:4096
	s_mov_b32 m0, s99
	v_lshl_add_u64 v[124:125], v[96:97], 0, s[54:55]
	global_load_lds_dwordx4 v[124:125], off
	s_add_u32 m0, s99, 0x2000
	v_lshl_add_u64 v[126:127], v[110:111], 0, s[54:55]
	global_load_lds_dwordx4 v[126:127], off
	s_add_u32 m0, s99, 0x4000
	v_lshl_add_u64 v[124:125], v[108:109], 0, s[54:55]
	global_load_lds_dwordx4 v[124:125], off
	s_add_u32 m0, s99, 0x6000
	v_lshl_add_u64 v[126:127], v[106:107], 0, s[54:55]
	global_load_lds_dwordx4 v[126:127], off
	s_add_u32 m0, s99, 0x8000
	v_lshl_add_u64 v[124:125], v[104:105], 0, s[54:55]
	global_load_lds_dwordx4 v[124:125], off
	s_add_u32 m0, s99, 0xa000
	v_lshl_add_u64 v[126:127], v[102:103], 0, s[54:55]
	global_load_lds_dwordx4 v[126:127], off
	s_branch .Ld1_g0
; DI void wait_vm0() { asm volatile("s_waitcnt vmcnt(0)" ::: "memory"); }
; DI void bar_() { __builtin_amdgcn_s_barrier(); }
; #define GLDS(gp, lp) __builtin_amdgcn_global_load_lds((const unsigned*)(gp), (__attribute__((address_space(3))) unsigned*)(lp), 16, 0, 0)
; #define SB_ __builtin_amdgcn_sched_barrier(0)
; template <int TM, int TN, int WM, int WN, bool SUMSQ, int NST, class AF, class BF, class AFN, class BFN>
; DI void gemm8x(f32x16 (&acc)[TM][TN], AF arow, BF brow, int K, char* smem, float& sumsq, bool pre, bool hasNext, AFN arowN, BFN browN) {
;     ...
;   auto compute = [&](const char* cur, char* nxt, bool issue, const bf16_t* q0, const bf16_t* q1, const bf16_t* q2, const bf16_t* q3,
;                      const bf16_t* s0, const bf16_t* s1, const bf16_t* s2, const bf16_t* s3) {
;     const char* As = cur + aoff;
;     const char* Bs = cur + boff;
;     char* l_ = nxt + t * 16; char* m_ = l_ + RA * LDR;
;     bf16x8 a0[TM], b0[TN], a1[TM], b1[TN];
;     ...
;     LOADF(a0, b0, 0);
;     LOADF(a1, b1, 1);
;     SB_;
;     if (issue) { if (a0v) GLDS(q0, l_); if (a1v) GLDS(q1, l_ + 8192); }
;     SB_;
;     __builtin_amdgcn_s_setprio(1);
;     MMF(a0, b0);
;     LOADF(a0, b0, 2);
;     SB_;
;     if (issue) { if (a2v) GLDS(q2, l_ + 16384); if (a3v) GLDS(q3, l_ + 24576); }
;     SB_;
;     MMF(a1, b1);
;     LOADF(a1, b1, 3);
;     SB_;
;     if (issue) { if (b0v) GLDS(s0, m_); if (b1v) GLDS(s1, m_ + 8192); }
;     SB_;
;     MMF(a0, b0);
;     SB_;
;     if (issue) { if (b2v) GLDS(s2, m_ + 16384); if (b3v) GLDS(s3, m_ + 24576); }
;     SB_;
;     MMF(a1, b1);
;     __builtin_amdgcn_s_setprio(0);
;   };
;   int sc_ = 0;
;   for (int kt = 0; kt < nk - 1; ++kt) {
;     SB_;
;     if (NST == 2) {
;       const int ko = (kt + 1) * 64;
;       compute(smem + (kt & 1) * STAGE, smem + ((kt + 1) & 1) * STAGE, true, pa0 + ko, pa1 + ko, pa2 + ko, pa3 + ko, pb0 + ko, pb1 + ko, pb2 + ko, pb3 + ko);
;       SB_;
;       wait_vm0(); bar_();
;     } else {
;       const int ko = (kt + 2) * 64; const bool iss = kt + 2 < nk;
;       const int sn = (sc_ == 0) ? 2 : sc_ - 1;
;       compute(smem + sc_ * STAGE, smem + sn * STAGE, iss, pa0 + ko, pa1 + ko, pa2 + ko, pa3 + ko, pb0 + ko, pb1 + ko, pb2 + ko, pb3 + ko);
;       SB_;
;       if (iss) asm volatile("s_waitcnt vmcnt(6)" ::: "memory"); else wait_vm0();
;       bar_();
;       sc_ = (sc_ == 2) ? 0 : sc_ + 1;
;     }
;   }
.Ld1_loop:
	s_mul_i32 s99, s93, 0xc000
	v_add_u32_e32 v123, s99, v118
	v_add_u32_e32 v122, s99, v117
	s_add_i32 s99, s99, 0xffff4000
	s_cmp_lg_u32 s93, 0
	s_cselect_b32 s99, s99, 0x18000
	s_add_i32 s99, s99, s98
	v_add_u32_e32 v131, v123, v116
	v_add_u32_e32 v130, v122, v116
	s_setprio 1
	v_mfma_f32_32x32x16_bf16 v[48:63], v[68:71], v[72:75], v[48:63]
	ds_read_b128 v[88:91], v131 offset:32768
	ds_read_b128 v[84:87], v130
	s_mov_b32 m0, s99
	v_lshl_add_u64 v[124:125], v[96:97], 0, s[54:55]
	global_load_lds_dwordx4 v[124:125], off
	v_mfma_f32_32x32x16_bf16 v[32:47], v[68:71], v[76:79], v[32:47]
	ds_read_b128 v[92:95], v131 offset:36864
	ds_read_b128 v[80:83], v130 offset:4096
	s_add_u32 m0, s99, 0x2000
	v_lshl_add_u64 v[126:127], v[110:111], 0, s[54:55]
	global_load_lds_dwordx4 v[126:127], off
	v_mfma_f32_32x32x16_bf16 v[16:31], v[64:67], v[72:75], v[16:31]
	s_add_u32 m0, s99, 0x4000
	v_lshl_add_u64 v[124:125], v[108:109], 0, s[54:55]
	global_load_lds_dwordx4 v[124:125], off
	s_add_u32 m0, s99, 0x6000
	v_lshl_add_u64 v[126:127], v[106:107], 0, s[54:55]
	global_load_lds_dwordx4 v[126:127], off
	v_mfma_f32_32x32x16_bf16 v[0:15], v[64:67], v[76:79], v[0:15]
	s_add_u32 m0, s99, 0x8000
	v_lshl_add_u64 v[124:125], v[104:105], 0, s[54:55]
	global_load_lds_dwordx4 v[124:125], off
	s_add_u32 m0, s99, 0xa000
	v_lshl_add_u64 v[126:127], v[102:103], 0, s[54:55]
	global_load_lds_dwordx4 v[126:127], off
.Ld1_g0:
	s_setprio 1
	v_add_u32_e32 v131, v123, v115
	v_add_u32_e32 v130, v122, v115
	s_waitcnt lgkmcnt(0)
	v_mfma_f32_32x32x16_bf16 v[48:63], v[84:87], v[88:91], v[48:63]
	ds_read_b128 v[72:75], v131 offset:32768
	ds_read_b128 v[68:71], v130
	v_mfma_f32_32x32x16_bf16 v[32:47], v[84:87], v[92:95], v[32:47]
	ds_read_b128 v[76:79], v131 offset:36864
	ds_read_b128 v[64:67], v130 offset:4096
	v_mfma_f32_32x32x16_bf16 v[16:31], v[80:83], v[88:91], v[16:31]
	v_mfma_f32_32x32x16_bf16 v[0:15], v[80:83], v[92:95], v[0:15]
	v_add_u32_e32 v131, v123, v114
	v_add_u32_e32 v130, v122, v114
	s_waitcnt lgkmcnt(0)
	v_mfma_f32_32x32x16_bf16 v[48:63], v[68:71], v[72:75], v[48:63]
	ds_read_b128 v[88:91], v131 offset:32768
	ds_read_b128 v[84:87], v130
	v_mfma_f32_32x32x16_bf16 v[32:47], v[68:71], v[76:79], v[32:47]
	ds_read_b128 v[92:95], v131 offset:36864
	ds_read_b128 v[80:83], v130 offset:4096
	v_mfma_f32_32x32x16_bf16 v[16:31], v[64:67], v[72:75], v[16:31]
	v_mfma_f32_32x32x16_bf16 v[0:15], v[64:67], v[76:79], v[0:15]
	v_add_u32_e32 v131, v123, v113
	v_add_u32_e32 v130, v122, v113
	s_waitcnt lgkmcnt(0)
	v_mfma_f32_32x32x16_bf16 v[48:63], v[84:87], v[88:91], v[48:63]
	ds_read_b128 v[72:75], v131 offset:32768
	ds_read_b128 v[68:71], v130
	v_mfma_f32_32x32x16_bf16 v[32:47], v[84:87], v[92:95], v[32:47]
	ds_read_b128 v[76:79], v131 offset:36864
	ds_read_b128 v[64:67], v130 offset:4096
	v_mfma_f32_32x32x16_bf16 v[16:31], v[80:83], v[88:91], v[16:31]
	v_mfma_f32_32x32x16_bf16 v[0:15], v[80:83], v[92:95], v[0:15]
	s_setprio 0
	s_waitcnt vmcnt(6) lgkmcnt(0)
	s_add_i32 s100, s93, 1
	s_cmp_lg_u32 s93, 2
	s_cselect_b32 s93, s100, 0
	s_add_u32 s54, s54, 0x80
	s_addc_u32 s55, s55, 0
	s_cmpk_lg_i32 s54, 0xf00
	s_barrier
	s_cbranch_scc1 .Ld1_loop
	v_mfma_f32_32x32x16_bf16 v[48:63], v[68:71], v[72:75], v[48:63]
	v_mfma_f32_32x32x16_bf16 v[32:47], v[68:71], v[76:79], v[32:47]
	v_mfma_f32_32x32x16_bf16 v[16:31], v[64:67], v[72:75], v[16:31]
	v_mfma_f32_32x32x16_bf16 v[0:15], v[64:67], v[76:79], v[0:15]

; template <int TM, int TN, int WM, int WN, bool SUMSQ, int NST, class AF, class BF, class AFN, class BFN>
; DI void gemm8x(f32x16 (&acc)[TM][TN], AF arow, BF brow, int K, char* smem, float& sumsq, bool pre, bool hasNext, AFN arowN, BFN browN) {
;     ...
;   const int t = tid_(), lane = t & 63, w = t >> 6, r = lane & 31, hh = lane >> 5;
;   const int wm = w % WM, wn = w / WM;
;   const int row0 = t >> 3;
;   const int c = (t & 7) ^ ((row0 >> 1) & 7);
;   const bool a0v = row0 < RA, a1v = row0 + 64 < RA, a2v = row0 + 128 < RA, a3v = row0 + 192 < RA;
;   const bool b0v = row0 < RB, b1v = row0 + 64 < RB, b2v = row0 + 128 < RB, b3v = row0 + 192 < RB;
;   const bf16_t* pa0 = arow(a0v ? row0 : 0) + c * 8;
;   const bf16_t* pa1 = arow(a1v ? row0 + 64 : 0) + c * 8;
;   const bf16_t* pa2 = arow(a2v ? row0 + 128 : 0) + c * 8;
;   const bf16_t* pa3 = arow(a3v ? row0 + 192 : 0) + c * 8;
;   const bf16_t* pb0 = brow(b0v ? row0 : 0) + c * 8;
;   const bf16_t* pb1 = brow(b1v ? row0 + 64 : 0) + c * 8;
;   const bf16_t* pb2 = brow(b2v ? row0 + 128 : 0) + c * 8;
;   const bf16_t* pb3 = brow(b3v ? row0 + 192 : 0) + c * 8;
;   if (!pre) {
;     char* l_ = smem + t * 16; char* m_ = l_ + RA * LDR;
;     if (a0v) GLDS(pa0, l_); if (a1v) GLDS(pa1, l_ + 8192); if (a2v) GLDS(pa2, l_ + 16384); if (a3v) GLDS(pa3, l_ + 24576);
;     if (b0v) GLDS(pb0, m_); if (b1v) GLDS(pb1, m_ + 8192); if (b2v) GLDS(pb2, m_ + 16384); if (b3v) GLDS(pb3, m_ + 24576);
;   }
;   if (NST == 3) {
;     char* l_ = smem + STAGE + t * 16; char* m_ = l_ + RA * LDR;
;     GLDS(pa0 + 64, l_); GLDS(pa1 + 64, l_ + 8192); GLDS(pa2 + 64, l_ + 16384); GLDS(pa3 + 64, l_ + 24576);
;     GLDS(pb0 + 64, m_); GLDS(pb1 + 64, m_ + 8192);
;     asm volatile("s_waitcnt vmcnt(6)" ::: "memory");
;   } else wait_vm0();
;   bar_();
;   const int nk = K >> 6;
;   const int sw = (r >> 1) & 7;
;   const int aoff = (wm * TM * 32 + r) * LDR, boff = RA * LDR + (wn * TN * 32 + r) * LDR;
;     ...
;     LOADF(a0, b0, 0);
;     LOADF(a1, b1, 1);
;     SB_;
;     if (issue) { if (a0v) GLDS(q0, l_); if (a1v) GLDS(q1, l_ + 8192); }
;     SB_;
;     __builtin_amdgcn_s_setprio(1);
;     MMF(a0, b0);
;     LOADF(a0, b0, 2);
;     SB_;
;     if (issue) { if (a2v) GLDS(q2, l_ + 16384); if (a3v) GLDS(q3, l_ + 24576); }
;     SB_;
;     MMF(a1, b1);
;     LOADF(a1, b1, 3);
;     SB_;
;     if (issue) { if (b0v) GLDS(s0, m_); if (b1v) GLDS(s1, m_ + 8192); }
;     SB_;
.LBB0_610:
	s_or_b64 exec, exec, s[52:53]
	v_ashrrev_i32_e32 v96, 6, v93
	v_lshrrev_b32_e32 v98, 30, v96
	v_readfirstlane_b32 s48, v94
	v_add_u32_e32 v98, v96, v98
	v_lshl_add_u64 v[72:73], v[72:73], 0, s[30:31]
	s_mov_b32 m0, s48
	v_ashrrev_i32_e32 v98, 2, v98
	global_load_lds_dwordx4 v[72:73], off
	v_lshl_add_u64 v[72:73], v[74:75], 0, s[30:31]
	v_readfirstlane_b32 s48, v95
	v_add_u32_e32 v74, 0x10000, v186
	v_mul_i32_i24_e32 v99, 4, v98
	s_mov_b32 m0, s48
	v_readfirstlane_b32 s48, v74
	v_add_u32_e32 v74, 0x12000, v186
	v_sub_u32_e32 v96, v96, v99
	v_add_u32_e32 v99, 0x14000, v186
	global_load_lds_dwordx4 v[72:73], off
	v_lshl_add_u64 v[72:73], v[78:79], 0, s[30:31]
	s_mov_b32 m0, s48
	v_readfirstlane_b32 s48, v74
	global_load_lds_dwordx4 v[72:73], off
	v_lshl_add_u64 v[72:73], v[82:83], 0, s[30:31]
	s_mov_b32 m0, s48
	v_readfirstlane_b32 s48, v99
	v_add_u32_e32 v74, 0x16000, v186
	global_load_lds_dwordx4 v[72:73], off
	v_lshl_add_u64 v[72:73], v[86:87], 0, s[30:31]
	s_mov_b32 m0, s48
	v_readfirstlane_b32 s48, v74
	global_load_lds_dwordx4 v[72:73], off
	v_lshl_add_u64 v[72:73], v[88:89], 0, s[30:31]
	s_mov_b32 m0, s48
	v_bfe_u32 v97, v93, 5, 1
	global_load_lds_dwordx4 v[72:73], off
	v_lshrrev_b32_e32 v72, 1, v93
	v_bfe_u32 v73, v93, 1, 3
	v_bitop3_b32 v72, v72, v97, 7 bitop3:0x6c
	v_lshlrev_b32_e32 v190, 4, v72
	v_bitop3_b32 v72, v97, v73, 2 bitop3:0x36
	v_lshlrev_b32_e32 v189, 4, v72
	v_bitop3_b32 v72, v97, v73, 4 bitop3:0x36
	v_lshlrev_b32_e32 v188, 4, v72
	v_bitop3_b32 v72, v97, v73, 6 bitop3:0x36
	v_lshlrev_b32_e32 v187, 4, v72
	v_and_b32_e32 v72, 7, v92
	v_lshlrev_b32_e32 v168, 4, v72
	s_add_u32 s48, s78, s50
	v_lshl_add_u64 v[64:65], v[64:65], 0, v[168:169]
	s_addc_u32 s49, s79, s51
	v_lshl_add_u64 v[170:171], s[48:49], 0, v[64:65]
	v_lshl_add_u64 v[64:65], s[42:43], 0, v[90:91]
	v_lshl_add_u64 v[64:65], v[64:65], 0, v[168:169]
	v_lshl_add_u64 v[172:173], s[40:41], 0, v[64:65]
	v_lshl_add_u64 v[64:65], s[42:43], 0, v[84:85]
	v_lshl_add_u64 v[64:65], v[64:65], 0, v[168:169]
	v_lshl_add_u64 v[174:175], s[40:41], 0, v[64:65]
	v_lshl_add_u64 v[64:65], s[42:43], 0, v[80:81]
	v_lshl_add_u64 v[64:65], v[64:65], 0, v[168:169]
	v_lshl_add_u64 v[176:177], s[40:41], 0, v[64:65]
	v_lshl_add_u64 v[64:65], s[42:43], 0, v[76:77]
	v_lshl_add_u64 v[64:65], v[64:65], 0, v[168:169]
	v_lshl_add_u64 v[178:179], s[40:41], 0, v[64:65]
	v_lshl_add_u64 v[64:65], v[70:71], 0, v[168:169]
	v_lshl_add_u64 v[180:181], s[48:49], 0, v[64:65]
	v_lshl_add_u64 v[64:65], v[68:69], 0, v[168:169]
	s_waitcnt vmcnt(6)
	v_lshlrev_b32_e32 v74, 7, v93
	v_lshl_add_u64 v[182:183], s[48:49], 0, v[64:65]
	v_lshl_add_u64 v[64:65], v[66:67], 0, v[168:169]
	v_and_b32_e32 v193, 0xf80, v74
	v_lshlrev_b32_e32 v194, 13, v98
	v_lshl_add_u64 v[184:185], s[48:49], 0, v[64:65]
	v_mov_b32_e32 v64, 0
	v_lshl_or_b32 v191, v96, 13, v193
	v_or_b32_e32 v192, v193, v194
	s_mov_b32 s42, 0
	s_mov_b64 s[48:49], 0
	v_mov_b32_e32 v65, v64
	v_mov_b32_e32 v66, v64
	v_mov_b32_e32 v67, v64
	v_mov_b32_e32 v68, v64
	v_mov_b32_e32 v69, v64
	v_mov_b32_e32 v70, v64
	v_mov_b32_e32 v71, v64
	v_mov_b32_e32 v72, v64
	v_mov_b32_e32 v73, v64
	v_mov_b32_e32 v74, v64
	v_mov_b32_e32 v75, v64
	v_mov_b32_e32 v76, v64
	v_mov_b32_e32 v77, v64
	v_mov_b32_e32 v78, v64
	v_mov_b32_e32 v79, v64
	v_mov_b32_e32 v80, v64
	v_mov_b32_e32 v81, v64
	v_mov_b32_e32 v82, v64
	v_mov_b32_e32 v83, v64
	v_mov_b32_e32 v84, v64
	v_mov_b32_e32 v85, v64
	v_mov_b32_e32 v86, v64
	v_mov_b32_e32 v87, v64
	v_mov_b32_e32 v88, v64
	v_mov_b32_e32 v89, v64
	v_mov_b32_e32 v90, v64
	v_mov_b32_e32 v91, v64
	v_mov_b32_e32 v92, v64
	v_mov_b32_e32 v93, v64
	v_mov_b32_e32 v94, v64
	v_mov_b32_e32 v95, v64
	v_mov_b32_e32 v96, v64
	v_mov_b32_e32 v97, v64
	v_mov_b32_e32 v98, v64
	v_mov_b32_e32 v99, v64
	v_mov_b32_e32 v100, v64
	v_mov_b32_e32 v101, v64
	v_mov_b32_e32 v102, v64
	v_mov_b32_e32 v103, v64
	v_mov_b32_e32 v104, v64
	v_mov_b32_e32 v105, v64
	v_mov_b32_e32 v106, v64
	v_mov_b32_e32 v107, v64
	v_mov_b32_e32 v108, v64
	v_mov_b32_e32 v109, v64
	v_mov_b32_e32 v110, v64
	v_mov_b32_e32 v111, v64
	v_mov_b32_e32 v112, v64
	v_mov_b32_e32 v113, v64
	v_mov_b32_e32 v114, v64
	v_mov_b32_e32 v115, v64
	v_mov_b32_e32 v116, v64
	v_mov_b32_e32 v117, v64
	v_mov_b32_e32 v118, v64
	v_mov_b32_e32 v119, v64
	v_mov_b32_e32 v120, v64
	v_mov_b32_e32 v121, v64
	v_mov_b32_e32 v122, v64
	v_mov_b32_e32 v123, v64
	v_mov_b32_e32 v124, v64
	v_mov_b32_e32 v125, v64
	v_mov_b32_e32 v126, v64
	v_mov_b32_e32 v127, v64
	s_barrier
	v_readfirstlane_b32 s98, v186
	s_mul_i32 s99, s42, 0xc000
	v_add_u32_e32 v167, s99, v192
	v_add_u32_e32 v166, s99, v191
	s_add_i32 s99, s99, 0xffff4000
	s_cmp_lg_u32 s42, 0
	s_cselect_b32 s99, s99, 0x18000
	s_add_i32 s99, s99, s98
	v_add_u32_e32 v165, v167, v190
	v_add_u32_e32 v164, v166, v190
	ds_read_b128 v[136:139], v165 offset:32768
	ds_read_b128 v[128:131], v164
	ds_read_b128 v[140:143], v165 offset:36864
	ds_read_b128 v[132:135], v164 offset:4096
	s_mov_b32 m0, s99
	v_lshl_add_u64 v[160:161], v[170:171], 0, s[48:49]
	global_load_lds_dwordx4 v[160:161], off
	s_add_u32 m0, s99, 0x2000
	v_lshl_add_u64 v[162:163], v[184:185], 0, s[48:49]
	global_load_lds_dwordx4 v[162:163], off
	s_add_u32 m0, s99, 0x4000
	v_lshl_add_u64 v[160:161], v[182:183], 0, s[48:49]
	global_load_lds_dwordx4 v[160:161], off
	s_add_u32 m0, s99, 0x6000
	v_lshl_add_u64 v[162:163], v[180:181], 0, s[48:49]
	global_load_lds_dwordx4 v[162:163], off
	s_add_u32 m0, s99, 0x8000
	v_lshl_add_u64 v[160:161], v[178:179], 0, s[48:49]
	global_load_lds_dwordx4 v[160:161], off
	s_add_u32 m0, s99, 0xa000
	v_lshl_add_u64 v[162:163], v[176:177], 0, s[48:49]
	global_load_lds_dwordx4 v[162:163], off
	s_branch .Ld2_g0
; DI void wait_vm0() { asm volatile("s_waitcnt vmcnt(0)" ::: "memory"); }
; DI void bar_() { __builtin_amdgcn_s_barrier(); }
; #define GLDS(gp, lp) __builtin_amdgcn_global_load_lds((const unsigned*)(gp), (__attribute__((address_space(3))) unsigned*)(lp), 16, 0, 0)
; #define SB_ __builtin_amdgcn_sched_barrier(0)
; template <int TM, int TN, int WM, int WN, bool SUMSQ, int NST, class AF, class BF, class AFN, class BFN>
; DI void gemm8x(f32x16 (&acc)[TM][TN], AF arow, BF brow, int K, char* smem, float& sumsq, bool pre, bool hasNext, AFN arowN, BFN browN) {
;     ...
;   auto compute = [&](const char* cur, char* nxt, bool issue, const bf16_t* q0, const bf16_t* q1, const bf16_t* q2, const bf16_t* q3,
;                      const bf16_t* s0, const bf16_t* s1, const bf16_t* s2, const bf16_t* s3) {
;     const char* As = cur + aoff;
;     const char* Bs = cur + boff;
;     char* l_ = nxt + t * 16; char* m_ = l_ + RA * LDR;
;     bf16x8 a0[TM], b0[TN], a1[TM], b1[TN];
;     ...
;     LOADF(a0, b0, 0);
;     LOADF(a1, b1, 1);
;     SB_;
;     if (issue) { if (a0v) GLDS(q0, l_); if (a1v) GLDS(q1, l_ + 8192); }
;     SB_;
;     __builtin_amdgcn_s_setprio(1);
;     MMF(a0, b0);
;     LOADF(a0, b0, 2);
;     SB_;
;     if (issue) { if (a2v) GLDS(q2, l_ + 16384); if (a3v) GLDS(q3, l_ + 24576); }
;     SB_;
;     MMF(a1, b1);
;     LOADF(a1, b1, 3);
;     SB_;
;     if (issue) { if (b0v) GLDS(s0, m_); if (b1v) GLDS(s1, m_ + 8192); }
;     SB_;
;     MMF(a0, b0);
;     SB_;
;     if (issue) { if (b2v) GLDS(s2, m_ + 16384); if (b3v) GLDS(s3, m_ + 24576); }
;     SB_;
;     MMF(a1, b1);
;     __builtin_amdgcn_s_setprio(0);
;   };
;   int sc_ = 0;
;   for (int kt = 0; kt < nk - 1; ++kt) {
;     SB_;
;     if (NST == 2) {
;       const int ko = (kt + 1) * 64;
;       compute(smem + (kt & 1) * STAGE, smem + ((kt + 1) & 1) * STAGE, true, pa0 + ko, pa1 + ko, pa2 + ko, pa3 + ko, pb0 + ko, pb1 + ko, pb2 + ko, pb3 + ko);
;       SB_;
;       wait_vm0(); bar_();
;     } else {
;       const int ko = (kt + 2) * 64; const bool iss = kt + 2 < nk;
;       const int sn = (sc_ == 0) ? 2 : sc_ - 1;
;       compute(smem + sc_ * STAGE, smem + sn * STAGE, iss, pa0 + ko, pa1 + ko, pa2 + ko, pa3 + ko, pb0 + ko, pb1 + ko, pb2 + ko, pb3 + ko);
;       SB_;
;       if (iss) asm volatile("s_waitcnt vmcnt(6)" ::: "memory"); else wait_vm0();
;       bar_();
;       sc_ = (sc_ == 2) ? 0 : sc_ + 1;
;     }
;   }
.Ld2_loop:
	s_mul_i32 s99, s42, 0xc000
	v_add_u32_e32 v167, s99, v192
	v_add_u32_e32 v166, s99, v191
	s_add_i32 s99, s99, 0xffff4000
	s_cmp_lg_u32 s42, 0
	s_cselect_b32 s99, s99, 0x18000
	s_add_i32 s99, s99, s98
	v_add_u32_e32 v165, v167, v190
	v_add_u32_e32 v164, v166, v190
	s_setprio 1
	v_mfma_f32_32x32x16_bf16 v[112:127], v[144:147], v[152:155], v[112:127]
	ds_read_b128 v[136:139], v165 offset:32768
	ds_read_b128 v[128:131], v164
	s_mov_b32 m0, s99
	v_lshl_add_u64 v[160:161], v[170:171], 0, s[48:49]
	global_load_lds_dwordx4 v[160:161], off
	v_mfma_f32_32x32x16_bf16 v[96:111], v[144:147], v[156:159], v[96:111]
	ds_read_b128 v[140:143], v165 offset:36864
	ds_read_b128 v[132:135], v164 offset:4096
	s_add_u32 m0, s99, 0x2000
	v_lshl_add_u64 v[162:163], v[184:185], 0, s[48:49]
	global_load_lds_dwordx4 v[162:163], off
	v_mfma_f32_32x32x16_bf16 v[80:95], v[148:151], v[152:155], v[80:95]
	s_add_u32 m0, s99, 0x4000
	v_lshl_add_u64 v[160:161], v[182:183], 0, s[48:49]
	global_load_lds_dwordx4 v[160:161], off
	s_add_u32 m0, s99, 0x6000
	v_lshl_add_u64 v[162:163], v[180:181], 0, s[48:49]
	global_load_lds_dwordx4 v[162:163], off
	v_mfma_f32_32x32x16_bf16 v[64:79], v[148:151], v[156:159], v[64:79]
	s_add_u32 m0, s99, 0x8000
	v_lshl_add_u64 v[160:161], v[178:179], 0, s[48:49]
	global_load_lds_dwordx4 v[160:161], off
	s_add_u32 m0, s99, 0xa000
	v_lshl_add_u64 v[162:163], v[176:177], 0, s[48:49]
	global_load_lds_dwordx4 v[162:163], off
.Ld2_g0:
	s_setprio 1
	v_add_u32_e32 v165, v167, v189
	v_add_u32_e32 v164, v166, v189
	s_waitcnt lgkmcnt(0)
	v_mfma_f32_32x32x16_bf16 v[112:127], v[128:131], v[136:139], v[112:127]
	ds_read_b128 v[152:155], v165 offset:32768
	ds_read_b128 v[144:147], v164
	v_mfma_f32_32x32x16_bf16 v[96:111], v[128:131], v[140:143], v[96:111]
	ds_read_b128 v[156:159], v165 offset:36864
	ds_read_b128 v[148:151], v164 offset:4096
	v_mfma_f32_32x32x16_bf16 v[80:95], v[132:135], v[136:139], v[80:95]
	v_mfma_f32_32x32x16_bf16 v[64:79], v[132:135], v[140:143], v[64:79]
	v_add_u32_e32 v165, v167, v188
	v_add_u32_e32 v164, v166, v188
	s_waitcnt lgkmcnt(0)
	v_mfma_f32_32x32x16_bf16 v[112:127], v[144:147], v[152:155], v[112:127]
	ds_read_b128 v[136:139], v165 offset:32768
	ds_read_b128 v[128:131], v164
	v_mfma_f32_32x32x16_bf16 v[96:111], v[144:147], v[156:159], v[96:111]
	ds_read_b128 v[140:143], v165 offset:36864
	ds_read_b128 v[132:135], v164 offset:4096
	v_mfma_f32_32x32x16_bf16 v[80:95], v[148:151], v[152:155], v[80:95]
	v_mfma_f32_32x32x16_bf16 v[64:79], v[148:151], v[156:159], v[64:79]
	v_add_u32_e32 v165, v167, v187
	v_add_u32_e32 v164, v166, v187
	s_waitcnt lgkmcnt(0)
	v_mfma_f32_32x32x16_bf16 v[112:127], v[128:131], v[136:139], v[112:127]
	ds_read_b128 v[152:155], v165 offset:32768
	ds_read_b128 v[144:147], v164
	v_mfma_f32_32x32x16_bf16 v[96:111], v[128:131], v[140:143], v[96:111]
	ds_read_b128 v[156:159], v165 offset:36864
	ds_read_b128 v[148:151], v164 offset:4096
	v_mfma_f32_32x32x16_bf16 v[80:95], v[132:135], v[136:139], v[80:95]
	v_mfma_f32_32x32x16_bf16 v[64:79], v[132:135], v[140:143], v[64:79]
	s_setprio 0
	s_waitcnt vmcnt(6) lgkmcnt(0)
	s_add_i32 s100, s42, 1
	s_cmp_lg_u32 s42, 2
	s_cselect_b32 s42, s100, 0
	s_add_u32 s48, s48, 0x80
	s_addc_u32 s49, s49, 0
	s_cmpk_lg_i32 s48, 0xf00
	s_barrier
	s_cbranch_scc1 .Ld2_loop
	v_mfma_f32_32x32x16_bf16 v[112:127], v[144:147], v[152:155], v[112:127]
	v_mfma_f32_32x32x16_bf16 v[96:111], v[144:147], v[156:159], v[96:111]
	v_mfma_f32_32x32x16_bf16 v[80:95], v[148:151], v[152:155], v[80:95]
	v_mfma_f32_32x32x16_bf16 v[64:79], v[148:151], v[156:159], v[64:79]

; __global__ void __launch_bounds__(NTH, 2) mega_kernel(Params p) {
;   cg::grid_group grid = cg::this_grid();
;   __shared__ __attribute__((aligned(16))) char smem[SMEM_BYTES];
	.amdhsa_kernel _Z11mega_kernel6Params
		.amdhsa_group_segment_fixed_size 147456
		.amdhsa_private_segment_fixed_size 0
		.amdhsa_kernarg_size 1424
		.amdhsa_user_sgpr_count 2
		.amdhsa_user_sgpr_dispatch_ptr 0
		.amdhsa_user_sgpr_queue_ptr 0
		.amdhsa_user_sgpr_kernarg_segment_ptr 1
		.amdhsa_user_sgpr_dispatch_id 0
		.amdhsa_user_sgpr_kernarg_preload_length 0
		.amdhsa_user_sgpr_kernarg_preload_offset 0
		.amdhsa_user_sgpr_private_segment_size 0
		.amdhsa_uses_dynamic_stack 0
		.amdhsa_enable_private_segment 0
		.amdhsa_system_sgpr_workgroup_id_x 1
		.amdhsa_system_sgpr_workgroup_id_y 0
		.amdhsa_system_sgpr_workgroup_id_z 0
		.amdhsa_system_sgpr_workgroup_info 0
		.amdhsa_system_vgpr_workitem_id 2
		.amdhsa_next_free_vgpr 253
		.amdhsa_next_free_sgpr 101
		.amdhsa_accum_offset 256
		.amdhsa_reserve_vcc 1
		.amdhsa_float_round_mode_32 0
		.amdhsa_float_round_mode_16_64 0
		.amdhsa_float_denorm_mode_32 3
		.amdhsa_float_denorm_mode_16_64 3
		.amdhsa_dx10_clamp 1
		.amdhsa_ieee_mode 1
		.amdhsa_fp16_overflow 0
		.amdhsa_tg_split 0
		.amdhsa_exception_fp_ieee_invalid_op 0
		.amdhsa_exception_fp_denorm_src 0
		.amdhsa_exception_fp_ieee_div_zero 0
		.amdhsa_exception_fp_ieee_overflow 0
		.amdhsa_exception_fp_ieee_underflow 0
		.amdhsa_exception_fp_ieee_inexact 0
		.amdhsa_exception_int_div_zero 0
	.end_amdhsa_kernel

; __global__ void __launch_bounds__(NTH, 2) mega_kernel(Params p) {
;   cg::grid_group grid = cg::this_grid();
;   __shared__ __attribute__((aligned(16))) char smem[SMEM_BYTES];
amdhsa.kernels:
  - .agpr_count:     0
    .args:
      - .offset:         0
        .size:           1168
        .value_kind:     by_value
      - .offset:         1168
        .size:           4
        .value_kind:     hidden_block_count_x
      - .offset:         1172
        .size:           4
        .value_kind:     hidden_block_count_y
      - .offset:         1176
        .size:           4
        .value_kind:     hidden_block_count_z
      - .offset:         1180
        .size:           2
        .value_kind:     hidden_group_size_x
      - .offset:         1182
        .size:           2
        .value_kind:     hidden_group_size_y
      - .offset:         1184
        .size:           2
        .value_kind:     hidden_group_size_z
      - .offset:         1186
        .size:           2
        .value_kind:     hidden_remainder_x
      - .offset:         1188
        .size:           2
        .value_kind:     hidden_remainder_y
      - .offset:         1190
        .size:           2
        .value_kind:     hidden_remainder_z
      - .offset:         1208
        .size:           8
        .value_kind:     hidden_global_offset_x
      - .offset:         1216
        .size:           8
        .value_kind:     hidden_global_offset_y
      - .offset:         1224
        .size:           8
        .value_kind:     hidden_global_offset_z
      - .offset:         1232
        .size:           2
        .value_kind:     hidden_grid_dims
      - .offset:         1256
        .size:           8
        .value_kind:     hidden_multigrid_sync_arg
    .group_segment_fixed_size: 147456
    .kernarg_segment_align: 8
    .kernarg_segment_size: 1424
    .language:       OpenCL C
    .language_version:
      - 2
      - 0
    .max_flat_workgroup_size: 512
    .name:           _Z11mega_kernel6Params
    .private_segment_fixed_size: 0
    .sgpr_count:     107
    .sgpr_spill_count: 4
    .symbol:         _Z11mega_kernel6Params.kd
    .uniform_work_group_size: 1
    .uses_dynamic_stack: false
    .vgpr_count:     253
    .vgpr_spill_count: 0
    .wavefront_size: 64
